# grid barrier release via the top arrival counter: all waiting workgroups poll the top-level arrival count against nx*(round+1) instead of a generation word, so the release is visible when the last arr
# baseline (speedup 1.0000x reference)
; __device__ __forceinline__ unsigned xb_ld(unsigned* p)              { return __hip_atomic_load(p, __ATOMIC_RELAXED, __HIP_MEMORY_SCOPE_AGENT); }
; __device__ __forceinline__ unsigned xb_add(unsigned* p, unsigned v) { return __hip_atomic_fetch_add(p, v, __ATOMIC_RELAXED, __HIP_MEMORY_SCOPE_AGENT); }
; #define XB_SPIN(cond, bar) do { unsigned _sp = 0; while (cond) { __builtin_amdgcn_s_sleep(1); \
;     if ((++_sp & 255u) == 0u) { if (xb_ld(&(bar)[XB_TMO])) break; if (_sp > XB_SPIN_CAP) { atomicAdd(&(bar)[XB_TMO], 1u); break; } } } } while (0)
; __device__ __forceinline__ void xcd_barrier(const XcdBarrier& b) {
;     ...
;         const unsigned old = xb_add(&bar[XB_XSUB(b.x)], 1u);
;         const unsigned gen = old / nloc;
;         if (old + 1u == (gen + 1u) * nloc) {
;             __builtin_amdgcn_fence(__ATOMIC_RELEASE, "agent");
;             asm volatile("s_waitcnt vmcnt(0)" ::: "memory");
;             const unsigned og = xb_add(&bar[XB_TOP], 1u);
;             const unsigned tg = og / nx;
;             if (og + 1u == (tg + 1u) * nx) xb_add(&bar[XB_TOPGEN], 1u);
;             else XB_SPIN(xb_ld(&bar[XB_TOPGEN]) == tg, bar);
;             __builtin_amdgcn_fence(__ATOMIC_ACQUIRE, "agent");
;             xb_add(&bar[XB_XGEN(b.x)], 1u);
;             asm volatile("s_waitcnt vmcnt(0)" ::: "memory");
;         } else {
;             XB_SPIN(xb_ld(&bar[XB_XGEN(b.x)]) == gen, bar);
;             __builtin_amdgcn_fence(__ATOMIC_ACQUIRE, "agent");
;             asm volatile("s_waitcnt vmcnt(0)" ::: "memory");
.LBB0_222:
	s_or_b64 exec, exec, s[6:7]
	v_cvt_f32_u32_e32 v4, v2
	s_waitcnt vmcnt(0)
	v_readfirstlane_b32 s6, v3
	v_sub_u32_e32 v3, 0, v2
	v_rcp_iflag_f32_e32 v4, v4
	v_add_u32_e32 v5, s6, v1
	v_mul_f32_e32 v4, 0x4f7ffffe, v4
	v_cvt_u32_f32_e32 v4, v4
	v_mul_lo_u32 v1, v3, v4
	v_mul_hi_u32 v1, v4, v1
	v_add_u32_e32 v1, v4, v1
	v_mul_hi_u32 v1, v5, v1
	v_mul_lo_u32 v3, v1, v2
	v_sub_u32_e32 v3, v5, v3
	v_add_u32_e32 v4, 1, v1
	v_cmp_ge_u32_e32 vcc, v3, v2
	s_nop 1
	v_cndmask_b32_e32 v1, v1, v4, vcc
	v_sub_u32_e32 v4, v3, v2
	v_cndmask_b32_e32 v3, v3, v4, vcc
	v_add_u32_e32 v4, 1, v1
	v_cmp_ge_u32_e32 vcc, v3, v2
	v_add_u32_e32 v3, 1, v5
	s_nop 0
	v_cndmask_b32_e32 v1, v1, v4, vcc
	v_mul_lo_u32 v4, v2, v1
	v_add_u32_e32 v2, v4, v2
	v_cmp_ne_u32_e32 vcc, v3, v2
	s_and_saveexec_b64 s[6:7], vcc
	s_xor_b64 s[6:7], exec, s[6:7]
	s_cbranch_execz .LBB0_236
	v_readlane_b32 s10, v249, 23
	v_readlane_b32 s11, v249, 24
	s_waitcnt lgkmcnt(0)
	v_add_u32_e32 v4, 1, v1
	v_mul_lo_u32 v4, v4, v0
	s_nop 3
	global_load_dword v0, v80, s[10:11] sc1
	s_waitcnt vmcnt(0)
	v_cmp_lt_u32_e32 vcc, v0, v4
	s_and_saveexec_b64 s[10:11], vcc
	s_cbranch_execz .LBB0_235
	s_mov_b32 s20, 1
	s_mov_b64 s[12:13], 0
	s_branch .LBB0_226

; __device__ __forceinline__ unsigned xb_ld(unsigned* p)              { return __hip_atomic_load(p, __ATOMIC_RELAXED, __HIP_MEMORY_SCOPE_AGENT); }
; #define XB_SPIN(cond, bar) do { unsigned _sp = 0; while (cond) { __builtin_amdgcn_s_sleep(1); \
;     if ((++_sp & 255u) == 0u) { if (xb_ld(&(bar)[XB_TMO])) break; if (_sp > XB_SPIN_CAP) { atomicAdd(&(bar)[XB_TMO], 1u); break; } } } } while (0)
; __device__ __forceinline__ void xcd_barrier(const XcdBarrier& b) {
;     ...
;             XB_SPIN(xb_ld(&bar[XB_XGEN(b.x)]) == gen, bar);
.LBB0_230:
	v_readlane_b32 s16, v249, 23
	v_readlane_b32 s17, v249, 24
	s_add_i32 s20, s20, 1
	s_mov_b64 s[18:19], -1
	s_nop 2
	global_load_dword v0, v80, s[16:17] sc1
	s_waitcnt vmcnt(0)
	v_cmp_ge_u32_e32 vcc, v0, v4
	s_orn2_b64 s[16:17], vcc, exec
	s_branch .LBB0_225

; __device__ __forceinline__ unsigned xb_ld(unsigned* p)              { return __hip_atomic_load(p, __ATOMIC_RELAXED, __HIP_MEMORY_SCOPE_AGENT); }
; __device__ __forceinline__ unsigned xb_add(unsigned* p, unsigned v) { return __hip_atomic_fetch_add(p, v, __ATOMIC_RELAXED, __HIP_MEMORY_SCOPE_AGENT); }
; #define XB_SPIN(cond, bar) do { unsigned _sp = 0; while (cond) { __builtin_amdgcn_s_sleep(1); \
;     if ((++_sp & 255u) == 0u) { if (xb_ld(&(bar)[XB_TMO])) break; if (_sp > XB_SPIN_CAP) { atomicAdd(&(bar)[XB_TMO], 1u); break; } } } } while (0)
; __device__ __forceinline__ void xcd_barrier(const XcdBarrier& b) {
;     ...
;             const unsigned og = xb_add(&bar[XB_TOP], 1u);
;             const unsigned tg = og / nx;
;             if (og + 1u == (tg + 1u) * nx) xb_add(&bar[XB_TOPGEN], 1u);
;             else XB_SPIN(xb_ld(&bar[XB_TOPGEN]) == tg, bar);
.LBB0_239:
	s_or_b64 exec, exec, s[10:11]
	s_waitcnt vmcnt(0)
	v_readfirstlane_b32 s6, v2
	v_cvt_f32_u32_e32 v2, v0
	v_sub_u32_e32 v3, 0, v0
	v_add_u32_e32 v1, s6, v1
	v_readlane_b32 s6, v249, 25
	v_rcp_iflag_f32_e32 v2, v2
	v_readlane_b32 s7, v249, 26
	s_mov_b64 s[10:11], -1
	v_mul_f32_e32 v2, 0x4f7ffffe, v2
	v_cvt_u32_f32_e32 v2, v2
	v_mul_lo_u32 v3, v3, v2
	v_mul_hi_u32 v3, v2, v3
	v_add_u32_e32 v2, v2, v3
	v_mul_hi_u32 v2, v1, v2
	v_mul_lo_u32 v3, v2, v0
	v_sub_u32_e32 v3, v1, v3
	v_cmp_ge_u32_e32 vcc, v3, v0
	v_add_u32_e32 v4, 1, v2
	v_add_u32_e32 v1, 1, v1
	v_cndmask_b32_e32 v2, v2, v4, vcc
	v_sub_u32_e32 v4, v3, v0
	v_cndmask_b32_e32 v3, v3, v4, vcc
	v_cmp_ge_u32_e32 vcc, v3, v0
	v_add_u32_e32 v3, 1, v2
	s_nop 0
	v_cndmask_b32_e32 v2, v2, v3, vcc
	v_mul_lo_u32 v3, v0, v2
	v_add_u32_e32 v0, v3, v0
	v_cmp_ne_u32_e32 vcc, v1, v0
	v_mov_b32_e32 v4, v0
	v_mov_b64_e32 v[0:1], s[6:7]
	s_and_saveexec_b64 s[6:7], vcc
	s_cbranch_execz .LBB0_251
	v_readlane_b32 s10, v249, 23
	v_readlane_b32 s11, v249, 24
	s_mov_b64 s[12:13], 0
	s_nop 3
	global_load_dword v0, v80, s[10:11] sc1
	s_waitcnt vmcnt(0)
	v_cmp_lt_u32_e32 vcc, v0, v4
	s_and_saveexec_b64 s[10:11], vcc
	s_cbranch_execz .LBB0_250
	s_mov_b32 s20, 1
	s_branch .LBB0_243

; __device__ __forceinline__ unsigned xb_ld(unsigned* p)              { return __hip_atomic_load(p, __ATOMIC_RELAXED, __HIP_MEMORY_SCOPE_AGENT); }
; __device__ __forceinline__ unsigned xb_add(unsigned* p, unsigned v) { return __hip_atomic_fetch_add(p, v, __ATOMIC_RELAXED, __HIP_MEMORY_SCOPE_AGENT); }
; #define XB_SPIN(cond, bar) do { unsigned _sp = 0; while (cond) { __builtin_amdgcn_s_sleep(1); \
;     if ((++_sp & 255u) == 0u) { if (xb_ld(&(bar)[XB_TMO])) break; if (_sp > XB_SPIN_CAP) { atomicAdd(&(bar)[XB_TMO], 1u); break; } } } } while (0)
; __device__ __forceinline__ void xcd_barrier(const XcdBarrier& b) {
;     ...
;         const unsigned old = xb_add(&bar[XB_XSUB(b.x)], 1u);
;         const unsigned gen = old / nloc;
;         if (old + 1u == (gen + 1u) * nloc) {
;             __builtin_amdgcn_fence(__ATOMIC_RELEASE, "agent");
;             asm volatile("s_waitcnt vmcnt(0)" ::: "memory");
;             const unsigned og = xb_add(&bar[XB_TOP], 1u);
;             const unsigned tg = og / nx;
;             if (og + 1u == (tg + 1u) * nx) xb_add(&bar[XB_TOPGEN], 1u);
;             else XB_SPIN(xb_ld(&bar[XB_TOPGEN]) == tg, bar);
;             __builtin_amdgcn_fence(__ATOMIC_ACQUIRE, "agent");
;             xb_add(&bar[XB_XGEN(b.x)], 1u);
;             asm volatile("s_waitcnt vmcnt(0)" ::: "memory");
;         } else {
;             XB_SPIN(xb_ld(&bar[XB_XGEN(b.x)]) == gen, bar);
;             __builtin_amdgcn_fence(__ATOMIC_ACQUIRE, "agent");
;             asm volatile("s_waitcnt vmcnt(0)" ::: "memory");
.LBB0_324:
	s_or_b64 exec, exec, s[6:7]
	v_cvt_f32_u32_e32 v4, v2
	s_waitcnt vmcnt(0)
	v_readfirstlane_b32 s6, v3
	v_sub_u32_e32 v3, 0, v2
	v_rcp_iflag_f32_e32 v4, v4
	v_add_u32_e32 v5, s6, v1
	v_mul_f32_e32 v4, 0x4f7ffffe, v4
	v_cvt_u32_f32_e32 v4, v4
	v_mul_lo_u32 v1, v3, v4
	v_mul_hi_u32 v1, v4, v1
	v_add_u32_e32 v1, v4, v1
	v_mul_hi_u32 v1, v5, v1
	v_mul_lo_u32 v3, v1, v2
	v_sub_u32_e32 v3, v5, v3
	v_add_u32_e32 v4, 1, v1
	v_cmp_ge_u32_e32 vcc, v3, v2
	s_nop 1
	v_cndmask_b32_e32 v1, v1, v4, vcc
	v_sub_u32_e32 v4, v3, v2
	v_cndmask_b32_e32 v3, v3, v4, vcc
	v_add_u32_e32 v4, 1, v1
	v_cmp_ge_u32_e32 vcc, v3, v2
	v_add_u32_e32 v3, 1, v5
	s_nop 0
	v_cndmask_b32_e32 v1, v1, v4, vcc
	v_mul_lo_u32 v4, v2, v1
	v_add_u32_e32 v2, v4, v2
	v_cmp_ne_u32_e32 vcc, v3, v2
	s_and_saveexec_b64 s[6:7], vcc
	s_xor_b64 s[6:7], exec, s[6:7]
	s_cbranch_execz .LBB0_338
	v_readlane_b32 s8, v249, 23
	v_readlane_b32 s9, v249, 24
	s_waitcnt lgkmcnt(0)
	v_add_u32_e32 v4, 1, v1
	v_mul_lo_u32 v4, v4, v0
	s_nop 3
	global_load_dword v0, v80, s[8:9] sc1
	s_waitcnt vmcnt(0)
	v_cmp_lt_u32_e32 vcc, v0, v4
	s_and_saveexec_b64 s[8:9], vcc
	s_cbranch_execz .LBB0_337
	s_mov_b32 s20, 1
	s_mov_b64 s[10:11], 0
	s_branch .LBB0_328

; __device__ __forceinline__ unsigned xb_ld(unsigned* p)              { return __hip_atomic_load(p, __ATOMIC_RELAXED, __HIP_MEMORY_SCOPE_AGENT); }
; #define XB_SPIN(cond, bar) do { unsigned _sp = 0; while (cond) { __builtin_amdgcn_s_sleep(1); \
;     if ((++_sp & 255u) == 0u) { if (xb_ld(&(bar)[XB_TMO])) break; if (_sp > XB_SPIN_CAP) { atomicAdd(&(bar)[XB_TMO], 1u); break; } } } } while (0)
; __device__ __forceinline__ void xcd_barrier(const XcdBarrier& b) {
;     ...
;             XB_SPIN(xb_ld(&bar[XB_XGEN(b.x)]) == gen, bar);
.LBB0_332:
	v_readlane_b32 s14, v249, 23
	v_readlane_b32 s15, v249, 24
	s_add_i32 s20, s20, 1
	s_mov_b64 s[16:17], -1
	s_nop 2
	global_load_dword v0, v80, s[14:15] sc1
	s_waitcnt vmcnt(0)
	v_cmp_ge_u32_e32 vcc, v0, v4
	s_orn2_b64 s[14:15], vcc, exec
	s_branch .LBB0_327

; __device__ __forceinline__ unsigned xb_ld(unsigned* p)              { return __hip_atomic_load(p, __ATOMIC_RELAXED, __HIP_MEMORY_SCOPE_AGENT); }
; __device__ __forceinline__ unsigned xb_add(unsigned* p, unsigned v) { return __hip_atomic_fetch_add(p, v, __ATOMIC_RELAXED, __HIP_MEMORY_SCOPE_AGENT); }
; #define XB_SPIN(cond, bar) do { unsigned _sp = 0; while (cond) { __builtin_amdgcn_s_sleep(1); \
;     if ((++_sp & 255u) == 0u) { if (xb_ld(&(bar)[XB_TMO])) break; if (_sp > XB_SPIN_CAP) { atomicAdd(&(bar)[XB_TMO], 1u); break; } } } } while (0)
; __device__ __forceinline__ void xcd_barrier(const XcdBarrier& b) {
;     ...
;             const unsigned og = xb_add(&bar[XB_TOP], 1u);
;             const unsigned tg = og / nx;
;             if (og + 1u == (tg + 1u) * nx) xb_add(&bar[XB_TOPGEN], 1u);
;             else XB_SPIN(xb_ld(&bar[XB_TOPGEN]) == tg, bar);
.LBB0_341:
	s_or_b64 exec, exec, s[8:9]
	s_waitcnt vmcnt(0)
	v_readfirstlane_b32 s6, v2
	v_cvt_f32_u32_e32 v2, v0
	v_sub_u32_e32 v3, 0, v0
	v_add_u32_e32 v1, s6, v1
	v_readlane_b32 s6, v249, 25
	v_rcp_iflag_f32_e32 v2, v2
	v_readlane_b32 s7, v249, 26
	s_mov_b64 s[8:9], -1
	v_mul_f32_e32 v2, 0x4f7ffffe, v2
	v_cvt_u32_f32_e32 v2, v2
	v_mul_lo_u32 v3, v3, v2
	v_mul_hi_u32 v3, v2, v3
	v_add_u32_e32 v2, v2, v3
	v_mul_hi_u32 v2, v1, v2
	v_mul_lo_u32 v3, v2, v0
	v_sub_u32_e32 v3, v1, v3
	v_cmp_ge_u32_e32 vcc, v3, v0
	v_add_u32_e32 v4, 1, v2
	v_add_u32_e32 v1, 1, v1
	v_cndmask_b32_e32 v2, v2, v4, vcc
	v_sub_u32_e32 v4, v3, v0
	v_cndmask_b32_e32 v3, v3, v4, vcc
	v_cmp_ge_u32_e32 vcc, v3, v0
	v_add_u32_e32 v3, 1, v2
	s_nop 0
	v_cndmask_b32_e32 v2, v2, v3, vcc
	v_mul_lo_u32 v3, v0, v2
	v_add_u32_e32 v0, v3, v0
	v_cmp_ne_u32_e32 vcc, v1, v0
	v_mov_b32_e32 v4, v0
	v_mov_b64_e32 v[0:1], s[6:7]
	s_and_saveexec_b64 s[6:7], vcc
	s_cbranch_execz .LBB0_353
	v_readlane_b32 s8, v249, 23
	v_readlane_b32 s9, v249, 24
	s_mov_b64 s[10:11], 0
	s_nop 3
	global_load_dword v0, v80, s[8:9] sc1
	s_waitcnt vmcnt(0)
	v_cmp_lt_u32_e32 vcc, v0, v4
	s_and_saveexec_b64 s[8:9], vcc
	s_cbranch_execz .LBB0_352
	s_mov_b32 s20, 1
	s_branch .LBB0_345
